# attention Q loads (read exactly once) marked non-temporal
# baseline (speedup 1.0000x reference)
.LBB0_404:
	s_ashr_i32 s77, s76, 31
	s_lshl_b64 s[46:47], s[76:77], 14
	s_or_b32 s46, s46, s91
	v_add_u32_e32 v2, s88, v139
	v_mov_b64_e32 v[0:1], s[46:47]
	v_mad_i64_i32 v[0:1], vcc, v2, s90, v[0:1]
	v_mov_b64_e32 v[2:3], s[42:43]
	v_mad_u64_u32 v[2:3], vcc, v0, s84, v[2:3]
	v_mov_b32_e32 v0, v3
	v_mad_u64_u32 v[0:1], vcc, v1, s84, v[0:1]
	v_mov_b32_e32 v3, v0
	s_ashr_i32 s9, s8, 31
	v_lshl_add_u64 v[0:1], s[8:9], 1, v[2:3]
	v_lshlrev_b32_e32 v2, 1, v134
	v_mov_b32_e32 v3, v88
	v_lshl_add_u64 v[0:1], v[0:1], 0, v[2:3]
	global_load_dwordx4 v[116:119], v[0:1], off nt
	global_load_dwordx4 v[120:123], v[0:1], off offset:32 nt
	global_load_dwordx4 v[124:127], v[0:1], off offset:64 nt
	global_load_dwordx4 v[128:131], v[0:1], off offset:96 nt
	v_add_u32_e32 v0, s87, v133
	v_mov_b32_e32 v89, v88
	v_cmp_gt_i32_e32 vcc, s66, v176
	v_cmp_lt_i32_e64 s[8:9], -1, v0
	v_mov_b32_e32 v90, v88
	v_mov_b32_e32 v91, v88
	v_mov_b64_e32 v[72:73], v[88:89]
	s_and_b64 vcc, vcc, s[8:9]
	v_mov_b32_e32 v64, 0
	v_mov_b64_e32 v[74:75], v[90:91]
	v_mov_b32_e32 v68, 0
	v_mov_b32_e32 v69, 0
	v_mov_b32_e32 v70, 0
	v_mov_b32_e32 v71, 0
	s_and_saveexec_b64 s[8:9], vcc
	s_cbranch_execz .LBB0_406
	v_mov_b64_e32 v[2:3], s[46:47]
	v_mad_u64_u32 v[0:1], vcc, v0, s90, v[2:3]
	v_mad_u64_u32 v[2:3], vcc, v0, s84, v[136:137]
	v_mov_b32_e32 v0, v3
	v_mad_u64_u32 v[0:1], vcc, v1, s84, v[0:1]
	v_mov_b32_e32 v3, v0
	v_lshl_add_u64 v[0:1], s[14:15], 1, v[2:3]
	s_mov_b32 s11, s15
	v_lshl_add_u64 v[2:3], s[10:11], 1, v[2:3]
	global_load_dwordx4 v[68:71], v[0:1], off
	global_load_dwordx4 v[72:75], v[2:3], off

.LBB0_1264:
	s_ashr_i32 s41, s40, 31
	s_lshl_b64 s[46:47], s[40:41], 14
	s_or_b32 s46, s46, s85
	v_add_u32_e32 v2, s80, v139
	v_mov_b64_e32 v[0:1], s[46:47]
	v_mad_i64_i32 v[0:1], vcc, v2, s84, v[0:1]
	v_mov_b64_e32 v[2:3], s[42:43]
	v_mad_u64_u32 v[2:3], vcc, v0, s72, v[2:3]
	v_mov_b32_e32 v0, v3
	v_mad_u64_u32 v[0:1], vcc, v1, s72, v[0:1]
	v_mov_b32_e32 v3, v0
	s_ashr_i32 s11, s10, 31
	v_lshl_add_u64 v[0:1], s[10:11], 1, v[2:3]
	v_lshlrev_b32_e32 v2, 1, v134
	v_mov_b32_e32 v3, v88
	v_lshl_add_u64 v[0:1], v[0:1], 0, v[2:3]
	global_load_dwordx4 v[116:119], v[0:1], off nt
	global_load_dwordx4 v[120:123], v[0:1], off offset:32 nt
	global_load_dwordx4 v[124:127], v[0:1], off offset:64 nt
	global_load_dwordx4 v[128:131], v[0:1], off offset:96 nt
	v_add_u32_e32 v0, s70, v133
	v_mov_b32_e32 v89, v88
	v_cmp_gt_i32_e32 vcc, s64, v176
	v_cmp_lt_i32_e64 s[10:11], -1, v0
	v_mov_b32_e32 v90, v88
	v_mov_b32_e32 v91, v88
	v_mov_b64_e32 v[72:73], v[88:89]
	s_and_b64 vcc, vcc, s[10:11]
	v_mov_b32_e32 v64, 0
	v_mov_b64_e32 v[74:75], v[90:91]
	v_mov_b32_e32 v68, 0
	v_mov_b32_e32 v69, 0
	v_mov_b32_e32 v70, 0
	v_mov_b32_e32 v71, 0
	s_and_saveexec_b64 s[10:11], vcc
	s_cbranch_execz .LBB0_1266
	v_mov_b64_e32 v[2:3], s[46:47]
	v_mad_u64_u32 v[0:1], vcc, v0, s84, v[2:3]
	v_mad_u64_u32 v[2:3], vcc, v0, s72, v[136:137]
	v_mov_b32_e32 v0, v3
	v_mad_u64_u32 v[0:1], vcc, v1, s72, v[0:1]
	v_mov_b32_e32 v3, v0
	v_lshl_add_u64 v[0:1], s[14:15], 1, v[2:3]
	s_mov_b32 s13, s15
	v_lshl_add_u64 v[2:3], s[12:13], 1, v[2:3]
	global_load_dwordx4 v[68:71], v[0:1], off
	global_load_dwordx4 v[72:75], v[2:3], off

.LBB0_2124:
	s_ashr_i32 s75, s74, 31
	s_lshl_b64 s[46:47], s[74:75], 14
	s_or_b32 s46, s46, s85
	v_add_u32_e32 v2, s80, v139
	v_mov_b64_e32 v[0:1], s[46:47]
	v_mad_i64_i32 v[0:1], vcc, v2, s84, v[0:1]
	v_mov_b64_e32 v[2:3], s[42:43]
	v_mad_u64_u32 v[2:3], vcc, v0, s72, v[2:3]
	v_mov_b32_e32 v0, v3
	v_mad_u64_u32 v[0:1], vcc, v1, s72, v[0:1]
	v_mov_b32_e32 v3, v0
	s_ashr_i32 s13, s12, 31
	v_lshl_add_u64 v[0:1], s[12:13], 1, v[2:3]
	v_lshlrev_b32_e32 v2, 1, v134
	v_mov_b32_e32 v3, v88
	v_lshl_add_u64 v[0:1], v[0:1], 0, v[2:3]
	global_load_dwordx4 v[116:119], v[0:1], off nt
	global_load_dwordx4 v[120:123], v[0:1], off offset:32 nt
	global_load_dwordx4 v[124:127], v[0:1], off offset:64 nt
	global_load_dwordx4 v[128:131], v[0:1], off offset:96 nt
	v_add_u32_e32 v0, s79, v133
	v_mov_b32_e32 v89, v88
	v_cmp_gt_i32_e32 vcc, s64, v176
	v_cmp_lt_i32_e64 s[12:13], -1, v0
	v_mov_b32_e32 v90, v88
	v_mov_b32_e32 v91, v88
	v_mov_b64_e32 v[72:73], v[88:89]
	s_and_b64 vcc, vcc, s[12:13]
	v_mov_b32_e32 v64, 0
	v_mov_b64_e32 v[74:75], v[90:91]
	v_mov_b32_e32 v68, 0
	v_mov_b32_e32 v69, 0
	v_mov_b32_e32 v70, 0
	v_mov_b32_e32 v71, 0
	s_and_saveexec_b64 s[12:13], vcc
	s_cbranch_execz .LBB0_2126
	v_mov_b64_e32 v[2:3], s[46:47]
	v_mad_u64_u32 v[0:1], vcc, v0, s84, v[2:3]
	v_mad_u64_u32 v[2:3], vcc, v0, s72, v[136:137]
	v_mov_b32_e32 v0, v3
	v_mad_u64_u32 v[0:1], vcc, v1, s72, v[0:1]
	v_mov_b32_e32 v3, v0
	v_lshl_add_u64 v[0:1], s[8:9], 1, v[2:3]
	s_mov_b32 s15, s9
	v_lshl_add_u64 v[2:3], s[14:15], 1, v[2:3]
	global_load_dwordx4 v[68:71], v[0:1], off
	global_load_dwordx4 v[72:75], v[2:3], off

.LBB0_2988:
	s_ashr_i32 s51, s50, 31
	s_lshl_b64 s[46:47], s[50:51], 14
	s_or_b32 s46, s46, s73
	v_add_u32_e32 v2, s70, v139
	v_mov_b64_e32 v[0:1], s[46:47]
	v_mad_i64_i32 v[0:1], s[84:85], v2, s72, v[0:1]
	v_mov_b64_e32 v[2:3], s[42:43]
	v_mad_u64_u32 v[2:3], s[84:85], v0, s66, v[2:3]
	v_mov_b32_e32 v0, v3
	v_mad_u64_u32 v[0:1], s[84:85], v1, s66, v[0:1]
	v_mov_b32_e32 v3, v0
	s_ashr_i32 s11, s10, 31
	v_lshl_add_u64 v[0:1], s[10:11], 1, v[2:3]
	v_lshlrev_b32_e32 v2, 1, v134
	v_mov_b32_e32 v3, v88
	v_lshl_add_u64 v[0:1], v[0:1], 0, v[2:3]
	global_load_dwordx4 v[116:119], v[0:1], off nt
	global_load_dwordx4 v[120:123], v[0:1], off offset:32 nt
	global_load_dwordx4 v[124:127], v[0:1], off offset:64 nt
	global_load_dwordx4 v[128:131], v[0:1], off offset:96 nt
	v_add_u32_e32 v0, s69, v133
	v_mov_b32_e32 v89, v88
	v_cmp_gt_i32_e32 vcc, s52, v176
	v_cmp_lt_i32_e64 s[10:11], -1, v0
	v_mov_b32_e32 v90, v88
	v_mov_b32_e32 v91, v88
	v_mov_b64_e32 v[72:73], v[88:89]
	s_and_b64 s[84:85], vcc, s[10:11]
	v_mov_b32_e32 v64, 0
	v_mov_b64_e32 v[74:75], v[90:91]
	v_mov_b32_e32 v68, 0
	v_mov_b32_e32 v69, 0
	v_mov_b32_e32 v70, 0
	v_mov_b32_e32 v71, 0
	s_and_saveexec_b64 s[10:11], s[84:85]
	s_cbranch_execz .LBB0_2990
	v_mov_b64_e32 v[2:3], s[46:47]
	v_mad_u64_u32 v[0:1], s[84:85], v0, s72, v[2:3]
	v_mad_u64_u32 v[2:3], s[84:85], v0, s66, v[136:137]
	v_mov_b32_e32 v0, v3
	v_mad_u64_u32 v[0:1], s[84:85], v1, s66, v[0:1]
	v_mov_b32_e32 v3, v0
	v_lshl_add_u64 v[0:1], s[16:17], 1, v[2:3]
	s_mov_b32 s13, s17
	v_lshl_add_u64 v[2:3], s[12:13], 1, v[2:3]
	global_load_dwordx4 v[68:71], v[0:1], off
	global_load_dwordx4 v[72:75], v[2:3], off
